# P9 split-K reduce loop limited to the 320 real rows of panels 32/33 (padding rows 8512..8703 are never output)
# baseline (speedup 1.0000x reference)
.LBB0_1313:
	s_or_b64 exec, exec, s[4:5]
	v_readlane_b32 s2, v255, 2
	v_readlane_b32 s6, v254, 15
	s_waitcnt lgkmcnt(0)
	v_or_b32_e32 v0, s2, v180
	v_lshl_add_u32 v2, s6, 9, v0
	s_mov_b32 s2, 0x50000
	v_cmp_gt_i32_e32 vcc, s2, v2
	s_barrier
	s_and_saveexec_b64 s[4:5], vcc
	v_readlane_b32 s20, v254, 23
	v_readlane_b32 s21, v254, 24
	v_readlane_b32 s22, v254, 25
	v_readlane_b32 s23, v254, 26
	s_cbranch_execz .LBB0_1316
	v_lshlrev_b32_e32 v0, 2, v0
	v_lshl_add_u32 v3, s6, 11, v0
	s_lshl_b32 s2, s33, 11
	s_mov_b64 s[6:7], 0
	s_mov_b32 s3, 0x1ffffff0
	v_mov_b32_e32 v1, 0
	s_brev_b32 s8, 32
	s_mov_b32 s9, 0x4040000
	s_mov_b32 s10, 0x4080000
	s_mov_b32 s11, 0x40c0000
	s_mov_b32 s12, 0x4100000
	s_mov_b32 s13, 0x4140000
	s_mov_b32 s14, 0x4180000
	s_mov_b32 s15, 0x41c0000
	s_mov_b32 s16, 0x4ffff
